# baseline (speedup 1.0000x reference)
; __device__ __forceinline__ void xcd_barrier(const XcdBarrier& b) {
;     asm volatile("s_waitcnt vmcnt(0)" ::: "memory");
;     __syncthreads();
;     if (threadIdx.x == 0) {
;         unsigned* bar = b.bar;
;         __builtin_amdgcn_s_waitcnt(0);
;         unsigned nloc = b.st[0], nx = b.st[1];
;         if (nloc == 0u) { xcd_barrier_complete(bar, b.x, nloc, nx); b.st[0] = nloc; b.st[1] = nx; }
; __global__ void __launch_bounds__(NTHR, 2) mega_fwd(Args a0) {
;     ...
;         if (ph + 1 < 15) { if (ph == 0) grid.sync(); else { XcdBarrier b2 = bar; asm volatile("" : "+s"(b2.bar)); xcd_barrier(b2); } }
.LBB0_872:
	v_readlane_b32 s0, v254, 18
	v_readlane_b32 s1, v254, 19
	s_and_b64 vcc, exec, s[0:1]
	v_readlane_b32 s2, v252, 4
	v_readlane_b32 s3, v252, 5
	s_waitcnt vmcnt(0)
	s_waitcnt vmcnt(0) lgkmcnt(0)
	s_barrier
	s_mov_b64 s[0:1], exec
	v_readlane_b32 s4, v252, 7
	v_readlane_b32 s5, v252, 8
	s_and_b64 s[4:5], s[0:1], s[4:5]
	s_mov_b64 exec, s[4:5]
	s_cbranch_execz .LBB0_918
	v_readlane_b32 s4, v253, 17
	s_waitcnt vmcnt(0) expcnt(0) lgkmcnt(0)
	s_nop 0
	v_mov_b32_e32 v0, s4
	ds_read_b32 v2, v0
	v_readlane_b32 s4, v253, 18
	s_waitcnt lgkmcnt(0)
	v_cmp_ne_u32_e32 vcc, 0, v2
	v_mov_b32_e32 v0, s4
	ds_read_b32 v0, v0
	s_cbranch_vccnz .LBB0_889
	s_add_u32 s4, s2, 0x1000
	s_addc_u32 s5, s3, 0
	s_add_u32 s6, s2, 0x1100
	s_addc_u32 s7, s3, 0
	s_add_u32 s8, s2, 0x1200
	s_addc_u32 s9, s3, 0
	s_add_u32 s10, s2, 0x1300
	s_addc_u32 s11, s3, 0
	s_mov_b32 s34, 1
	s_mov_b64 s[12:13], 0
	s_branch .LBB0_878
